# weight-conversion phase: rotated workgroup-to-tile assignment of the input-proj and down-proj weight transposes to balance per-workgroup tile counts
# speedup vs baseline: 1.0052x; 1.0052x over previous
; #define LAS __attribute__((address_space(3)))
; #define OPQV(x) asm volatile("" : "+v"(x))
; DEV int map_col(int n, int Nsrc, int mode) {
;     if (mode == 1) { if (n < 4096) { const int U = n >> 8, c = n & 255; const int fq = (c >> 3) & 3; const int t = (c >> 7) * 2 + ((c >> 2) & 1), ch = 64 * U + ((c >> 5) & 3) * 16 + (fq & 1) * 8 + (fq >> 1) * 4 + (c & 3); return t * 1024 + ch; }
;         if (n < 5632) return n;
;         if (n < 6656) return 6704 + (n - 5632);
;         if (n < 10752) { const int m = n - 6656, U = m >> 8, c = m & 255;
;             const int fq = (c >> 3) & 3; const int t = (c >> 7) * 2 + ((c >> 2) & 1), ch = 64 * U + ((c >> 5) & 3) * 16 + (fq & 1) * 8 + (fq >> 1) * 4 + (c & 3);
;             return (t == 0 ? 7728 : t == 1 ? 8752 : t == 2 ? 9776 : 5680) + ch; }
;         if (n < 10800) return n - 5120; return -1; }
; template <int NW>
; DEV void convT(LAS unsigned char* lds, const float* src, int K, int Nsrc, bf16_t* dst, int Npad, int mode, int rot) {
;     LAS float* tile = (LAS float*)lds;
;     int tid = threadIdx.x; OPQV(tid); const int G = gridDim.x;
;     constexpr int PW = NW + 1, NL = NW * 64 / 512, RPI = 512 / NW, TPN = 512 / NW, KS = 64 / TPN;
;     const int ntk = K / 64, ntn = Npad / NW, ntiles = ntk * ntn;
;     const int n = tid % NW, kr = tid / NW;
;     int tix = (blockIdx.x + G - (rot % G)) % G;
;     float ld[NL];
;     if (tix < ntiles) { const int n0 = (tix / ntk) * NW, k0 = (tix % ntk) * 64; const int sc = map_col(n0 + n, Nsrc, mode);
; #pragma unroll
;         for (int i = 0; i < NL; ++i) ld[i] = sc >= 0 ? __builtin_nontemporal_load(src + (size_t)(k0 + i * RPI + kr) * Nsrc + sc) : 0.f; }
.LBB0_499:
	s_or_b64 exec, exec, s[4:5]
	v_cvt_f32_u32_e32 v0, s71
	s_load_dwordx2 s[4:5], s[0:1], 0x18
	s_mul_i32 s7, s14, 0x2a30000
	s_mul_hi_i32 s6, s14, 0x2a30000
	v_rcp_iflag_f32_e32 v0, v0
	s_waitcnt vmcnt(0)
	v_mov_b32_e32 v20, v210
	s_waitcnt lgkmcnt(0)
	s_add_u32 s4, s4, s7
	s_addc_u32 s5, s5, s6
	v_mul_f32_e32 v0, 0x4f7ffffe, v0
	v_cvt_u32_f32_e32 v0, v0
	s_sub_i32 s6, 0, s71
	s_add_i32 s12, s71, s2
	v_readfirstlane_b32 s13, v0
	s_mul_i32 s6, s6, s13
	s_mul_hi_u32 s6, s13, s6
	s_add_i32 s13, s13, s6
	s_mul_hi_u32 s6, s12, s13
	s_mul_i32 s6, s6, s71
	s_sub_i32 s6, s12, s6
	s_sub_i32 s7, s6, s71
	s_cmp_ge_u32 s6, s71
	s_cselect_b32 s6, s7, s6
	s_waitcnt vmcnt(0)
	v_ashrrev_i32_e32 v24, 31, v20
	s_sub_i32 s7, s6, s71
	v_lshrrev_b32_e32 v2, 25, v24
	s_cmp_ge_u32 s6, s71
	v_add_u32_e32 v2, v20, v2
	s_cselect_b32 s20, s7, s6
	v_ashrrev_i32_e32 v21, 7, v2
	v_and_b32_e32 v2, 0xffffff80, v2
	s_add_i32 s20, s20, 0xc0
.Lrot_win_chk:
	s_cmp_lt_u32 s20, s71
	s_cbranch_scc1 .Lrot_win_ok
	s_sub_i32 s20, s20, s71
	s_branch .Lrot_win_chk
.Lrot_win_ok:
	s_cmpk_lt_i32 s20, 0x560
	s_cselect_b64 s[6:7], -1, 0
	s_cmpk_gt_i32 s20, 0x55f
	v_sub_u32_e32 v22, v20, v2
	s_cbranch_scc1 .LBB0_552
	s_ashr_i32 s8, s20, 31
	s_lshr_b32 s8, s8, 28
	s_add_i32 s8, s20, s8
	s_ashr_i32 s8, s8, 4
	v_lshl_add_u32 v0, s8, 7, v22
	v_cmp_lt_i32_e32 vcc, s58, v0
	s_and_saveexec_b64 s[40:41], vcc
	s_xor_b64 s[40:41], exec, s[40:41]
	s_cbranch_execz .LBB0_517
	s_movk_i32 s15, 0x15ff
	v_cmp_lt_u32_e32 vcc, s15, v0
	s_and_saveexec_b64 s[42:43], vcc
	s_cbranch_execz .LBB0_516
	s_movk_i32 s15, 0x19ff
	v_cmp_lt_u32_e32 vcc, s15, v0
	s_and_saveexec_b64 s[44:45], vcc
	s_xor_b64 s[44:45], exec, s[44:45]
	s_cbranch_execz .LBB0_513
	s_movk_i32 s15, 0x29ff
	v_cmp_lt_u32_e32 vcc, s15, v0
	s_and_saveexec_b64 s[46:47], vcc
	s_xor_b64 s[46:47], exec, s[46:47]
	s_movk_i32 s15, 0x2a30
	v_add_u32_e32 v2, 0xffffec00, v0
	v_cmp_gt_u32_e32 vcc, s15, v0
	s_nop 1
	v_cndmask_b32_e32 v0, -1, v2, vcc
	s_andn2_saveexec_b64 s[46:47], s[46:47]
	s_cbranch_execz .LBB0_1343
	v_lshrrev_b32_e32 v2, 6, v0
	v_bfe_u32 v3, v0, 2, 1
	v_and_or_b32 v3, v2, 2, v3
	v_cmp_lt_i32_e32 vcc, 0, v3
	v_mov_b32_e32 v2, 0x1e30
	s_and_saveexec_b64 s[48:49], vcc
	s_cbranch_execz .LBB0_512
	v_cmp_ne_u32_e32 vcc, 1, v3
	s_and_saveexec_b64 s[50:51], vcc
	s_xor_b64 s[50:51], exec, s[50:51]
	v_cmp_eq_u32_e32 vcc, 2, v3
	v_mov_b32_e32 v2, 0x1630
	v_mov_b32_e32 v3, 0x2630
	v_cndmask_b32_e32 v2, v2, v3, vcc
	s_andn2_saveexec_b64 s[50:51], s[50:51]
	v_mov_b32_e32 v2, 0x2230
	s_or_b64 exec, exec, s[50:51]

; template <int NW>
; DEV void convT(LAS unsigned char* lds, const float* src, int K, int Nsrc, bf16_t* dst, int Npad, int mode, int rot) {
;     ...
;     int tix = (blockIdx.x + G - (rot % G)) % G;
;     float ld[NL];
;     if (tix < ntiles) { const int n0 = (tix / ntk) * NW, k0 = (tix % ntk) * 64; const int sc = map_col(n0 + n, Nsrc, mode);
; #pragma unroll
;         for (int i = 0; i < NL; ++i) ld[i] = sc >= 0 ? __builtin_nontemporal_load(src + (size_t)(k0 + i * RPI + kr) * Nsrc + sc) : 0.f; }
.LBB0_965:
	s_load_dwordx2 s[4:5], s[0:1], 0x98
	v_mov_b32_e32 v23, v210
	s_mul_i32 s7, s14, 0xc00000
	s_mul_hi_i32 s6, s14, 0xc00000
	v_ashrrev_i32_e32 v25, 31, v23
	s_waitcnt lgkmcnt(0)
	s_add_u32 s4, s4, s7
	v_lshrrev_b32_e32 v0, 25, v25
	s_addc_u32 s5, s5, s6
	v_add_u32_e32 v0, v23, v0
	v_ashrrev_i32_e32 v22, 7, v0
	v_and_b32_e32 v0, 0xffffff80, v0
	s_add_i32 s21, s21, 0x80
.Lrot_wdn_chk:
	s_cmp_lt_u32 s21, s71
	s_cbranch_scc1 .Lrot_wdn_ok
	s_sub_i32 s21, s21, s71
	s_branch .Lrot_wdn_chk
.Lrot_wdn_ok:
	s_cmpk_lt_i32 s21, 0x180
	s_cselect_b64 s[6:7], -1, 0
	s_cmpk_gt_i32 s21, 0x17f
	v_sub_u32_e32 v24, v23, v0
	s_cbranch_scc1 .LBB0_999
	s_mul_hi_i32 s15, s21, 0x2aaaaaab
	s_lshr_b32 s36, s15, 31
	s_ashr_i32 s15, s15, 3
	s_add_i32 s15, s15, s36
	s_mul_i32 s36, s15, 48
	s_sub_i32 s36, s21, s36
	v_lshl_add_u32 v0, s15, 7, v24
	v_lshl_add_u32 v18, s36, 6, v22
	v_cmp_lt_i32_e64 s[40:41], -1, v0
	v_lshl_add_u64 v[20:21], v[0:1], 2, s[4:5]
	s_waitcnt vmcnt(0)
	v_mov_b32_e32 v3, 0
	v_ashrrev_i32_e32 v19, 31, v18
	v_mov_b32_e32 v2, 0
	s_and_saveexec_b64 s[38:39], s[40:41]
	s_cbranch_execz .LBB0_968
	v_lshlrev_b64 v[4:5], 12, v[18:19]
	v_lshl_add_u64 v[4:5], v[20:21], 0, v[4:5]
	global_load_dword v2, v[4:5], off nt
